# v32 + P2->P3 grid barrier replaced by 4-WG (b,h) group barrier (RAW) + 8 arrival counters for the QKV/O overlay (WAR)
# speedup vs baseline: 1.0127x; 1.0023x over previous
; __device__ __forceinline__ unsigned xb_ld(unsigned* p)              { return __hip_atomic_load(p, __ATOMIC_RELAXED, __HIP_MEMORY_SCOPE_AGENT); }
; __device__ __forceinline__ unsigned xb_add(unsigned* p, unsigned v) { return __hip_atomic_fetch_add(p, v, __ATOMIC_RELAXED, __HIP_MEMORY_SCOPE_AGENT); }
; #define XB_SPIN(cond, bar) do { unsigned _sp = 0; while (cond) { __builtin_amdgcn_s_sleep(1); \
;     if ((++_sp & 255u) == 0u) { if (xb_ld(&(bar)[XB_TMO])) break; if (_sp > XB_SPIN_CAP) { atomicAdd(&(bar)[XB_TMO], 1u); break; } } } } while (0)
; __device__ __forceinline__ void xcd_barrier(const XcdBarrier& b) {
;     asm volatile("s_waitcnt vmcnt(0)" ::: "memory");
;     __syncthreads();
;     if (threadIdx.x == 0) {
;         unsigned* bar = b.bar;
;         __builtin_amdgcn_s_waitcnt(0);
;         unsigned nloc = b.st[0], nx = b.st[1];
;         if (nloc == 0u) { xcd_barrier_complete(bar, b.x, nloc, nx); b.st[0] = nloc; b.st[1] = nx; }
;         const unsigned old = xb_add(&bar[XB_XSUB(b.x)], 1u);
;         const unsigned gen = old / nloc;
;         if (old + 1u == (gen + 1u) * nloc) {
;             __builtin_amdgcn_fence(__ATOMIC_RELEASE, "agent");
;             asm volatile("s_waitcnt vmcnt(0)" ::: "memory");
;             const unsigned og = xb_add(&bar[XB_TOP], 1u);
;             const unsigned tg = og / nx;
;             if (og + 1u == (tg + 1u) * nx) xb_add(&bar[XB_TOPGEN], 1u);
;             else XB_SPIN(xb_ld(&bar[XB_TOPGEN]) == tg, bar);
;             __builtin_amdgcn_fence(__ATOMIC_ACQUIRE, "agent");
;             xb_add(&bar[XB_XGEN(b.x)], 1u);
;             asm volatile("s_waitcnt vmcnt(0)" ::: "memory");
;         } else {
;             XB_SPIN(xb_ld(&bar[XB_XGEN(b.x)]) == gen, bar);
;             __builtin_amdgcn_fence(__ATOMIC_ACQUIRE, "agent");
;             asm volatile("s_waitcnt vmcnt(0)" ::: "memory");
;         }
;     }
;     __syncthreads();
; }
.LBB0_724:
	v_readlane_b32 s4, v255, 5
	v_readlane_b32 s5, v255, 6
	s_cmp_lt_i32 s5, 4
	s_cbranch_scc1 .LBB0_776
	v_readlane_b32 s0, v255, 9
	s_cmp_eq_u32 s0, 0
	s_cbranch_scc1 .Lgd_grid
	v_readfirstlane_b32 s0, v0
	s_cmp_ge_u32 s0, 64
	s_cbranch_scc1 .Lgd_nold
	v_readlane_b32 s0, v255, 3
	s_lshr_b32 s1, s0, 5
	s_lshl_b32 s1, s1, 5
	s_bfe_u32 s0, s0, 0x30002
	s_add_i32 s0, s0, s1
	s_lshl_b32 s0, s0, 2
	s_add_i32 s0, s0, 0x51000
	v_and_b32_e32 v1, 3, v0
	v_lshl_add_u32 v1, v1, 5, s0
	global_load_dword v1, v1, s[26:27] sc1
.Lgd_nold:
	s_waitcnt vmcnt(0)
	s_barrier
	v_readlane_b32 s4, v1, 0
	v_cmp_ne_u32_e32 vcc, s4, v1
	s_and_b32 s5, vcc_lo, 0xf
	s_cmp_eq_u32 s5, 0
	s_cselect_b32 s5, 1, 0
	s_cmp_lg_u32 s4, 0
	s_cselect_b32 s98, s5, 0
	v_cmp_eq_u32_e32 vcc, 0, v0
	s_and_saveexec_b64 s[2:3], vcc
	s_cbranch_execz .LBB0_775
	s_cmp_eq_u32 s98, 1
	s_cbranch_scc1 .Lgd_noflush
	buffer_wbl2 sc1
	s_waitcnt vmcnt(0)
.Lgd_noflush:
	v_readlane_b32 s0, v255, 3
	s_lshr_b32 s1, s0, 5
	s_lshl_b32 s1, s1, 8
	s_add_i32 s1, s1, 0x54000
	s_lshr_b32 s0, s0, 2
	s_lshl_b32 s0, s0, 8
	s_add_i32 s0, s0, 0x55000
	v_mov_b32_e32 v2, 1
	v_mov_b32_e32 v1, s1
	global_atomic_add v1, v2, s[26:27]
	v_mov_b32_e32 v5, s0
	global_atomic_add v5, v2, s[26:27]
	s_mov_b32 exec_lo, 0x1ff
	s_mov_b32 exec_hi, 0
	s_mov_b32 s4, 0x54000
	v_lshl_add_u32 v1, v254, 8, s4
	v_mov_b32_e32 v4, 32
	v_mov_b32_e32 v5, s0
	v_cmp_eq_u32_e32 vcc, 8, v254
	v_cndmask_b32_e32 v1, v1, v5, vcc
	v_cndmask_b32_e64 v4, v4, 4, vcc
	s_mov_b32 s6, 0
.Lgd_spin:
	global_load_dword v3, v1, s[26:27] sc1
	s_waitcnt vmcnt(0)
	v_cmp_ge_u32_e32 vcc, v3, v4
	s_andn2_b64 s[4:5], exec, vcc
	s_cbranch_scc0 .Lgd_done
	s_sleep 1
	s_add_i32 s6, s6, 1
	s_cmp_lt_u32 s6, 0x4000
	s_cbranch_scc1 .Lgd_spin

; __device__ __forceinline__ unsigned xb_ld(unsigned* p)              { return __hip_atomic_load(p, __ATOMIC_RELAXED, __HIP_MEMORY_SCOPE_AGENT); }
; __device__ __forceinline__ unsigned xb_add(unsigned* p, unsigned v) { return __hip_atomic_fetch_add(p, v, __ATOMIC_RELAXED, __HIP_MEMORY_SCOPE_AGENT); }
; #define XB_SPIN(cond, bar) do { unsigned _sp = 0; while (cond) { __builtin_amdgcn_s_sleep(1); \
;     if ((++_sp & 255u) == 0u) { if (xb_ld(&(bar)[XB_TMO])) break; if (_sp > XB_SPIN_CAP) { atomicAdd(&(bar)[XB_TMO], 1u); break; } } } } while (0)
; __device__ __forceinline__ void xcd_barrier(const XcdBarrier& b) {
;     asm volatile("s_waitcnt vmcnt(0)" ::: "memory");
;     __syncthreads();
;     if (threadIdx.x == 0) {
;         unsigned* bar = b.bar;
;         __builtin_amdgcn_s_waitcnt(0);
;         unsigned nloc = b.st[0], nx = b.st[1];
;         if (nloc == 0u) { xcd_barrier_complete(bar, b.x, nloc, nx); b.st[0] = nloc; b.st[1] = nx; }
;         const unsigned old = xb_add(&bar[XB_XSUB(b.x)], 1u);
;         const unsigned gen = old / nloc;
;         if (old + 1u == (gen + 1u) * nloc) {
;             __builtin_amdgcn_fence(__ATOMIC_RELEASE, "agent");
;             asm volatile("s_waitcnt vmcnt(0)" ::: "memory");
;             const unsigned og = xb_add(&bar[XB_TOP], 1u);
;             const unsigned tg = og / nx;
;             if (og + 1u == (tg + 1u) * nx) xb_add(&bar[XB_TOPGEN], 1u);
;             else XB_SPIN(xb_ld(&bar[XB_TOPGEN]) == tg, bar);
;             __builtin_amdgcn_fence(__ATOMIC_ACQUIRE, "agent");
;             xb_add(&bar[XB_XGEN(b.x)], 1u);
;             asm volatile("s_waitcnt vmcnt(0)" ::: "memory");
;         } else {
;             XB_SPIN(xb_ld(&bar[XB_XGEN(b.x)]) == gen, bar);
;             __builtin_amdgcn_fence(__ATOMIC_ACQUIRE, "agent");
;             asm volatile("s_waitcnt vmcnt(0)" ::: "memory");
;         }
;     }
;     __syncthreads();
; }
.Lgd_grid:
	s_waitcnt vmcnt(0)
	v_cmp_eq_u32_e32 vcc, 0, v0
	s_waitcnt vmcnt(0)
	s_barrier
	s_and_saveexec_b64 s[2:3], vcc
	s_cbranch_execz .LBB0_775
	v_readlane_b32 s0, v255, 8
	s_waitcnt vmcnt(0) expcnt(0) lgkmcnt(0)
	s_nop 0
	v_mov_b32_e32 v1, s0
	ds_read_b32 v3, v1
	ds_read_b32 v1, v1 offset:4
	s_waitcnt lgkmcnt(1)
	v_cmp_ne_u32_e32 vcc, 0, v3
	s_cbranch_vccnz .LBB0_743
	v_readlane_b32 s4, v255, 0
	v_readlane_b32 s5, v255, 1
	s_load_dwordx2 s[0:1], s[4:5], 0x4
	s_add_u32 s4, s26, 0x4200
	s_addc_u32 s5, s27, 0
	s_add_u32 s6, s26, 0x4400
	s_addc_u32 s7, s27, 0
	s_add_u32 s8, s26, 0x4500
	s_addc_u32 s9, s27, 0
	s_add_u32 s16, s26, 0x4600
	s_addc_u32 s17, s27, 0
	s_add_u32 s18, s26, 0x4700
	s_addc_u32 s19, s27, 0
	s_add_u32 s20, s26, 0x4800
	s_addc_u32 s21, s27, 0
	s_add_u32 s28, s26, 0x4900
	s_addc_u32 s29, s27, 0
	s_add_u32 s30, s26, 0x4a00
	s_addc_u32 s31, s27, 0
	s_add_u32 s38, s26, 0x4b00
	s_addc_u32 s39, s27, 0
	s_add_u32 s40, s26, 0x4c00
	s_addc_u32 s41, s27, 0
	s_add_u32 s42, s26, 0x4d00
	s_addc_u32 s43, s27, 0
	s_add_u32 s44, s26, 0x4e00
	s_addc_u32 s45, s27, 0
	s_add_u32 s46, s26, 0x4f00
	s_addc_u32 s47, s27, 0
	s_add_u32 s48, s26, 0x5000
	s_addc_u32 s49, s27, 0
	s_add_u32 s50, s26, 0x5100
	s_addc_u32 s51, s27, 0
	s_add_u32 s66, s26, 0x5200
	s_addc_u32 s67, s27, 0
	s_waitcnt lgkmcnt(0)
	s_mul_i32 s0, s0, s52
	s_add_u32 s68, s26, 0x5300
	s_mul_i32 s0, s0, s1
	s_addc_u32 s69, s27, 0
	s_mov_b32 s1, 1
	v_mov_b32_e32 v17, 0
	s_branch .LBB0_729
